# FF2 stream-K segment lengths 40 (32 workgroups) / 36 (192) instead of 38 (64) / 36 (160), classes of 4 / 12 time-aligned workgroups per XCD on compact tile blocks
# baseline (speedup 1.0000x reference)
.LBB0_411:
	s_or_b64 exec, exec, s[0:1]
	s_cmpk_lt_i32 s2, 0x330
	s_mul_hi_i32 s0, s2, 0xa0a0a0a1
	s_cselect_b64 s[26:27], -1, 0
	s_add_i32 s0, s0, s2
	s_lshr_b32 s1, s0, 31
	s_lshr_b32 s0, s0, 9
	s_add_i32 s0, s0, s1
	s_mulk_i32 s0, 0x330
	s_sub_i32 s0, s2, s0
	s_sext_i32_i16 s1, s0
	s_bfe_u32 s1, s1, 0x3001c
	s_add_i32 s1, s0, s1
	s_sext_i32_i16 s3, s1
	s_and_b32 s1, s1, 0xfff8
	s_ashr_i32 s6, s3, 3
	s_sub_i32 s8, s0, s1
	s_sub_i32 s80, s94, 48
	s_sub_i32 s0, s2, 48
	s_cmp_gt_u32 s2, 47
	s_cselect_b32 s81, s0, 0x10000000
	s_cmpk_lt_i32 s81, 0x198
	s_cselect_b64 s[0:1], -1, 0
	v_writelane_b32 v245, s0, 3
	s_waitcnt lgkmcnt(0)
	v_mov_b32_e32 v0, 0xe0
	v_sub_co_u32_e32 v0, vcc, s2, v0
	v_writelane_b32 v245, s1, 4
	s_mul_hi_i32 s0, s81, 0xa0a0a0a1
	s_add_i32 s0, s0, s81
	s_lshr_b32 s1, s0, 31
	s_lshr_b32 s0, s0, 8
	s_add_i32 s0, s0, s1
	s_mulk_i32 s0, 0x198
	s_sub_i32 s0, s81, s0
	s_sext_i32_i16 s1, s0
	s_bfe_u32 s1, s1, 0x3001c
	s_add_i32 s1, s0, s1
	s_sext_i32_i16 s3, s1
	s_and_b32 s1, s1, 0xfff8
	s_ashr_i32 s5, s3, 3
	s_sub_i32 s7, s0, s1
	s_cmpk_lt_i32 s2, 0x110
	s_cselect_b64 s[0:1], -1, 0
	v_writelane_b32 v245, s0, 5
	s_bfe_u32 s87, s2, 0x50002
	s_lshr_b32 s3, s2, 2
	v_writelane_b32 v245, s1, 6
	s_and_b32 s0, s2, 3
	s_lshl_b32 s89, s87, 6
	s_lshl_b32 s1, s0, 2
	s_lshl_b32 s0, s0, 8
	s_cmp_lg_u32 s87, 0
	v_writelane_b32 v245, s1, 7
	s_cselect_b64 s[36:37], -1, 0
	s_cmp_eq_u32 s87, 31
	v_writelane_b32 v245, s0, 8
	s_cselect_b64 s[38:39], -1, 0
	s_lshl_b32 s0, s2, 8
	s_and_b32 s0, s0, 0x300
	s_cmp_eq_u32 s87, 0
	v_writelane_b32 v245, s0, 9
	s_cselect_b64 s[0:1], -1, 0
	v_writelane_b32 v245, s0, 10
	s_cmp_gt_u32 s87, 1
	s_movk_i32 s93, 0x67
	v_writelane_b32 v245, s1, 11
	s_cselect_b64 s[0:1], -1, 0
	v_writelane_b32 v245, s0, 12
	s_cmp_gt_u32 s87, 2
	v_mov_b32_e32 v185, 0
	v_writelane_b32 v245, s1, 13
	s_cselect_b64 s[0:1], -1, 0
	v_writelane_b32 v245, s0, 14
	s_cmp_gt_u32 s87, 3
	v_mov_b32_e32 v216, 0x358637bd
	v_writelane_b32 v245, s1, 15
	s_cselect_b64 s[0:1], -1, 0
	v_writelane_b32 v245, s0, 16
	s_cmp_gt_u32 s87, 4
	v_mov_b32_e32 v217, 0x1000
	v_writelane_b32 v245, s1, 17
	s_cselect_b64 s[0:1], -1, 0
	v_writelane_b32 v245, s0, 18
	s_cmp_gt_u32 s87, 5
	v_mov_b32_e32 v218, 0x2000
	v_writelane_b32 v245, s1, 19
	s_cselect_b64 s[0:1], -1, 0
	v_writelane_b32 v245, s0, 20
	s_cmp_gt_u32 s87, 6
	v_mov_b32_e32 v219, 0x11083000
	v_writelane_b32 v245, s1, 21
	s_cselect_b64 s[0:1], -1, 0
	v_writelane_b32 v245, s0, 22
	s_cmp_gt_u32 s87, 7
	v_mov_b32_e32 v220, 1
	v_writelane_b32 v245, s1, 23
	s_cselect_b64 s[0:1], -1, 0
	v_writelane_b32 v245, s0, 24
	s_cmp_gt_u32 s87, 8
	v_mov_b32_e32 v222, 0x3000
	v_writelane_b32 v245, s1, 25
	s_cselect_b64 s[0:1], -1, 0
	s_cmp_gt_u32 s87, 9
	s_cselect_b64 s[40:41], -1, 0
	s_cmp_gt_u32 s87, 10
	s_cselect_b64 s[42:43], -1, 0
	s_cmp_gt_u32 s87, 11
	s_cselect_b64 s[44:45], -1, 0
	s_cmp_gt_u32 s87, 12
	s_cselect_b64 s[46:47], -1, 0
	s_cmp_gt_u32 s87, 13
	v_writelane_b32 v245, s0, 26
	s_cselect_b64 s[48:49], -1, 0
	s_cmp_gt_u32 s87, 14
	v_writelane_b32 v245, s1, 27
	s_cselect_b64 s[0:1], -1, 0
	v_writelane_b32 v245, s0, 28
	s_cmp_gt_u32 s87, 15
	v_mov_b32_e32 v223, 0x2200
	v_writelane_b32 v245, s1, 29
	s_cselect_b64 s[0:1], -1, 0
	v_writelane_b32 v245, s0, 30
	s_cmp_gt_u32 s87, 16
	s_movk_i32 s90, 0x4000
	v_writelane_b32 v245, s1, 31
	s_cselect_b64 s[0:1], -1, 0
	v_writelane_b32 v245, s0, 32
	s_cmp_gt_u32 s87, 17
	s_movk_i32 s68, 0x4800
	v_writelane_b32 v245, s1, 33
	s_cselect_b64 s[0:1], -1, 0
	v_writelane_b32 v245, s0, 34
	s_cmp_gt_u32 s87, 18
	s_mov_b32 s69, 0xffff0000
	v_writelane_b32 v245, s1, 35
	s_cselect_b64 s[0:1], -1, 0
	v_writelane_b32 v245, s0, 36
	s_cmp_gt_u32 s87, 19
	s_movk_i32 s50, 0x3000
	v_writelane_b32 v245, s1, 37
	s_cselect_b64 s[0:1], -1, 0
	v_writelane_b32 v245, s0, 38
	s_cmp_gt_u32 s87, 20
	s_mov_b32 s52, 0
	v_writelane_b32 v245, s1, 39
	s_cselect_b64 s[0:1], -1, 0
	v_writelane_b32 v245, s0, 40
	s_cmp_gt_u32 s87, 21
	s_mov_b32 s97, 0
	v_writelane_b32 v245, s1, 41
	s_cselect_b64 s[0:1], -1, 0
	v_writelane_b32 v245, s0, 42
	s_cmp_gt_u32 s87, 22
	s_nop 0
	v_writelane_b32 v245, s1, 43
	s_cselect_b64 s[0:1], -1, 0
	v_writelane_b32 v245, s0, 44
	s_cmp_gt_u32 s87, 23
	s_barrier
	v_writelane_b32 v245, s1, 45
	s_cselect_b64 s[0:1], -1, 0
	v_writelane_b32 v245, s0, 46
	s_cmp_gt_u32 s87, 24
	s_nop 0
	v_writelane_b32 v245, s1, 47
	s_cselect_b64 s[0:1], -1, 0
	v_writelane_b32 v245, s0, 48
	s_cmp_gt_u32 s87, 25
	s_nop 0
	v_writelane_b32 v245, s1, 49
	s_cselect_b64 s[0:1], -1, 0
	v_writelane_b32 v245, s0, 50
	s_cmp_gt_u32 s87, 26
	s_nop 0
	v_writelane_b32 v245, s1, 51
	s_cselect_b64 s[0:1], -1, 0
	v_writelane_b32 v245, s0, 52
	s_cmp_gt_u32 s87, 27
	s_nop 0
	v_writelane_b32 v245, s1, 53
	s_cselect_b64 s[0:1], -1, 0
	v_writelane_b32 v245, s0, 54
	s_cmp_gt_u32 s87, 28
	s_nop 0
	v_writelane_b32 v245, s1, 55
	s_cselect_b64 s[0:1], -1, 0
	v_writelane_b32 v245, s0, 56
	s_cmp_gt_u32 s87, 29
	s_nop 0
	v_writelane_b32 v245, s1, 57
	s_cselect_b64 s[0:1], -1, 0
	v_writelane_b32 v245, s0, 58
	s_nop 1
	v_writelane_b32 v245, s1, 59
	v_sub_co_u32_e64 v214, s[0:1], s2, 32
	s_xor_b64 s[0:1], s[0:1], -1
	s_nop 0
	v_writelane_b32 v245, s0, 60
	s_nop 1
	v_writelane_b32 v245, s1, 61
	s_sub_i32 s0, s94, 32
	v_writelane_b32 v245, s0, 62
	s_lshl_b32 s0, s3, 6
	s_addk_i32 s0, 0x2000
	v_writelane_b32 v245, s0, 63
	s_lshl_b32 s0, s3, 3
	s_cmpk_lt_i32 s2, 0x198
	v_writelane_b32 v244, s0, 0
	s_mul_hi_i32 s0, s2, 0x78787879
	s_cselect_b64 s[10:11], -1, 0
	v_writelane_b32 v244, s10, 1
	s_lshr_b32 s1, s0, 31
	s_ashr_i32 s0, s0, 6
	v_writelane_b32 v244, s11, 2
	s_add_i32 s10, s0, s1
	s_mul_i32 s0, s10, 0x88
	s_sub_i32 s0, s2, s0
	s_bfe_u32 s1, s0, 0x3001c
	s_add_i32 s1, s0, s1
	s_and_b32 s3, s1, 0xfff8
	s_sub_i32 s9, s0, s3
	s_sext_i32_i16 s0, s1
	s_ashr_i32 s11, s10, 31
	s_ashr_i32 s14, s0, 3
	s_lshl_b64 s[0:1], s[10:11], 11
	v_writelane_b32 v244, s0, 3
	s_nop 1
	v_writelane_b32 v244, s1, 4
	s_mov_b32 s0, s10
	v_writelane_b32 v244, s0, 5
	s_nop 1
	v_writelane_b32 v244, s1, 6
	s_lshl_b64 s[0:1], s[10:11], 21
	v_writelane_b32 v244, s0, 7
	s_cmpk_lt_i32 s2, 0x88
	s_nop 0
	v_writelane_b32 v244, s1, 8
	s_cselect_b64 s[0:1], -1, 0
	v_writelane_b32 v244, s0, 9
	s_cmpk_gt_u32 s2, 0x87
	s_nop 0
	v_writelane_b32 v244, s1, 10
	s_cselect_b64 s[0:1], -1, 0
	v_writelane_b32 v244, s0, 11
	s_nop 1
	v_writelane_b32 v244, s1, 12
	s_add_i32 s0, s84, 0xfffffbc0
	v_writelane_b32 v244, s0, 13
	s_add_i32 s0, s88, 0xfffffbc0
	s_cmpk_lt_i32 s2, 0x200
	v_writelane_b32 v244, s0, 14
	s_cselect_b64 s[0:1], -1, 0
	v_writelane_b32 v244, s0, 15
	s_ashr_i32 s3, s2, 31
	s_and_b32 s12, s2, 15
	v_writelane_b32 v244, s1, 16
	s_lshr_b32 s0, s3, 23
	s_add_i32 s0, s2, s0
	s_and_b32 s0, s0, 0xfe00
	s_sub_i32 s0, s2, s0
	s_sext_i32_i16 s1, s0
	s_bfe_u32 s1, s1, 0x3001c
	s_add_i32 s1, s0, s1
	s_and_b32 s4, s1, 0xfff8
	s_sub_i32 s15, s0, s4
	s_sext_i32_i16 s0, s1
	s_ashr_i32 s16, s0, 3
	v_readfirstlane_b32 s0, v0
	s_ashr_i32 s4, s0, 4
	s_add_i32 s10, s4, 32
	s_lshl_b32 s0, s4, 5
	s_ashr_i32 s11, s10, 31
	s_lshl_b32 s13, s12, 19
	s_ashr_i32 s1, s0, 31
	s_lshl_b32 s17, s15, 6
	v_writelane_b32 v244, s13, 17
	s_lshl_b64 s[18:19], s[10:11], 19
	v_writelane_b32 v244, s18, 18
	s_cmp_gt_i32 s4, -1
	s_nop 0
	v_writelane_b32 v244, s19, 19
	s_cselect_b64 s[18:19], -1, 0
	v_writelane_b32 v244, s18, 20
	s_ashr_i32 s11, s10, 3
	s_lshl_b32 s13, s10, 8
	v_writelane_b32 v244, s19, 21
	v_writelane_b32 v244, s11, 22
	s_lshl_b32 s10, s12, 8
	v_writelane_b32 v244, s10, 23
	s_and_b32 s56, s2, 7
	s_lshr_b32 s57, s2, 3
	s_sub_i32 s57, s57, 4
	s_lshr_b32 s58, s57, 1
	s_lshl_b32 s58, s58, 4
	s_lshl_b32 s56, s56, 1
	s_add_i32 s58, s58, s56
	s_and_b32 s57, s57, 1
	s_add_i32 s58, s58, s57
	s_add_i32 s58, s58, 32
	s_sub_i32 s57, s2, 32
	s_cmpk_lt_u32 s57, 0xc0
	s_cselect_b32 s54, s58, s2
	s_mov_b32 s55, 0
	s_lshl_b32 s10, s54, 4
	s_add_i32 s11, s10, 0x1200
	s_mul_i32 s10, s54, 36
	s_add_i32 s18, s10, 0x80
	s_or_b32 s10, s13, 0x80
	v_writelane_b32 v244, s10, 24
	s_or_b32 s10, s13, 0x90
	v_writelane_b32 v244, s10, 25
	s_or_b32 s10, s13, 0xa0
	v_writelane_b32 v244, s10, 26
	v_writelane_b32 v244, s13, 27
	s_or_b32 s10, s13, 0xb0
	v_writelane_b32 v244, s10, 28
	s_add_i32 s10, s54, 1
	s_cmpk_lt_u32 s10, 0xe0
	s_cselect_b32 s12, 36, 16
	s_cmp_gt_i32 s54, 30
	s_cselect_b32 s19, s12, 40
	s_add_i32 s12, s54, 2
	s_cmpk_lt_u32 s12, 0xe0
	s_cselect_b32 s12, 36, 16
	s_cmp_gt_i32 s54, 29
	s_cselect_b32 s12, s12, 40
	s_add_i32 s20, s19, s12
	s_cmpk_gt_u32 s2, 0xdf
	s_cselect_b64 s[12:13], -1, 0
	v_writelane_b32 v244, s12, 29
	s_nop 1
	v_writelane_b32 v244, s13, 30
	s_and_b64 s[12:13], s[12:13], exec
	s_cselect_b32 s21, 16, 36
	s_cselect_b32 s22, s11, s18
	s_and_b64 s[12:13], vcc, exec
	s_cselect_b32 s11, s18, s11
	s_cmp_lt_i32 s54, 32
	s_mul_i32 s12, s54, 40
	s_cselect_b32 s13, s12, s22
	s_cselect_b32 s18, s12, s11
	s_cselect_b32 s21, 40, s21
	s_and_b32 s12, s13, 62
	s_ashr_i32 s11, s13, 6
	s_sub_i32 s12, 64, s12
	s_cmp_lt_u32 s12, s21
	v_mov_b32_e32 v0, s12
	s_cselect_b64 s[12:13], -1, 0
	v_sub_u32_e64 v0, s21, v0 clamp
	v_writelane_b32 v244, s12, 31
	s_add_i32 s11, s11, 1
	v_writelane_b32 v244, s13, 32
	s_lshr_b32 s92, s11, 2
	s_and_b32 s28, s11, 3
	s_sub_i32 s60, s11, 20
	s_mul_i32 s61, s60, 57
	s_lshr_b32 s61, s61, 9
	s_mul_i32 s62, s61, 9
	s_sub_i32 s62, s60, s62
	s_mul_i32 s62, s62, 3
	s_lshr_b32 s63, s61, 2
	s_add_i32 s62, s62, s63
	s_and_b32 s63, s61, 3
	s_cmpk_lt_u32 s11, 0x80
	s_cselect_b32 s92, s62, s92
	s_cselect_b32 s28, s63, s28
	s_mul_i32 s63, s11, 13
	s_lshr_b32 s63, s63, 6
	s_mul_i32 s62, s63, 5
	s_sub_i32 s62, s11, s62
	s_add_i32 s62, s62, 27
	s_cmpk_lt_u32 s11, 20
	s_cselect_b32 s92, s62, s92
	s_cselect_b32 s28, s63, s28
	v_readfirstlane_b32 s11, v0
	s_nop 1
	v_writelane_b32 v244, s11, 33
	s_sub_i32 s11, 64, s11
	s_cmp_gt_u32 s11, s19
	s_cselect_b32 s22, 2, 1
	s_cmp_gt_u32 s11, s20
	s_cselect_b64 s[12:13], -1, 0
	s_cmp_lg_u64 s[12:13], 0
	s_addc_u32 s11, s22, 0
	v_writelane_b32 v244, s11, 34
	s_ashr_i32 s11, s10, 31
	s_lshl_b64 s[10:11], s[10:11], 17
	v_writelane_b32 v244, s10, 35
	s_lshl_b64 s[12:13], s[54:55], 17
	s_nop 0
	v_writelane_b32 v244, s11, 36
	s_sext_i32_i16 s10, s8
	s_cmp_lt_i32 s10, 0
	s_cselect_b32 s10, s93, 0x66
	s_mul_i32 s8, s10, s8
	s_add_i32 s8, s8, s6
	s_sext_i32_i16 s6, s8
	s_mulk_i32 s6, 0x2aab
	s_lshr_b32 s10, s6, 31
	s_ashr_i32 s6, s6, 21
	s_add_i32 s6, s6, s10
	s_mul_i32 s10, s6, 0xc0
	s_sext_i32_i16 s6, s6
	s_lshl_b32 s11, s6, 3
	v_writelane_b32 v244, s12, 37
	s_sub_i32 s6, 34, s11
	s_sub_i32 s10, s8, s10
	v_writelane_b32 v244, s13, 38
	s_min_u32 s12, s6, 8
	s_sext_i32_i16 s6, s7
	s_cmp_lt_i32 s6, 0
	s_cselect_b32 s6, 52, 51
	s_mul_i32 s6, s6, s7
	s_add_i32 s6, s6, s5
	s_sext_i32_i16 s5, s6
	s_mulk_i32 s5, 0x2aab
	s_lshr_b32 s7, s5, 31
	s_ashr_i32 s5, s5, 20
	s_add_i32 s5, s5, s7
	s_mul_i32 s7, s5, 0x60
	s_sext_i32_i16 s5, s5
	s_lshl_b32 s5, s5, 3
	s_sub_i32 s13, s6, s7
	s_sub_i32 s6, 34, s5
	s_min_u32 s22, s6, 8
	s_sext_i32_i16 s6, s9
	s_cmp_lt_i32 s6, 0
	s_cselect_b32 s6, 18, 17
	s_mul_i32 s6, s6, s9
	s_add_i32 s6, s6, s14
	s_sext_i32_i16 s7, s6
	s_bfe_u32 s7, s7, 0x5001a
	s_add_i32 s7, s6, s7
	s_and_b32 s8, s7, 0xffe0
	s_sub_i32 s14, s6, s8
	s_sext_i32_i16 s6, s7
	s_ashr_i32 s6, s6, 5
	s_lshl_b32 s23, s6, 3
	s_sub_i32 s6, 34, s23
	s_min_u32 s24, s6, 8
	s_sext_i32_i16 s6, s15
	s_cmp_lt_i32 s6, 0
	s_mulk_i32 s15, 0x41
	s_cselect_b32 s6, s15, s17
	s_add_i32 s6, s6, s16
	s_sext_i32_i16 s7, s6
	s_bfe_u32 s7, s7, 0x70018
	s_add_i32 s7, s6, s7
	s_and_b32 s8, s7, 0xff80
	s_sub_i32 s6, s6, s8
	s_bfe_i32 s8, s6, 0x80000
	s_bfe_u32 s8, s8, 0x3000c
	s_add_i32 s8, s6, s8
	s_and_b32 s9, s8, 0xf8
	s_sext_i32_i16 s7, s7
	s_sub_i32 s6, s6, s9
	s_and_b32 s15, s18, 62
	s_ashr_i32 s7, s7, 7
	s_bfe_i32 s8, s8, 0x80000
	s_sub_i32 s9, 64, s15
	s_lshl_b32 s7, s7, 3
	s_sext_i32_i16 s8, s8
	s_sext_i32_i8 s6, s6
	s_min_u32 s9, s9, s21
	s_add_i32 s30, s7, s6
	s_ashr_i32 s6, s8, 3
	v_writelane_b32 v244, s6, 39
	s_lshr_b32 s6, s8, 3
	s_lshr_b32 s56, s18, 6
	s_lshr_b32 s18, s56, 2
	s_and_b32 s17, s56, 3
	s_sub_i32 s60, s56, 20
	s_mul_i32 s61, s60, 57
	s_lshr_b32 s61, s61, 9
	s_mul_i32 s62, s61, 9
	s_sub_i32 s62, s60, s62
	s_mul_i32 s62, s62, 3
	s_lshr_b32 s63, s61, 2
	s_add_i32 s62, s62, s63
	s_and_b32 s63, s61, 3
	s_cmpk_lt_u32 s56, 0x80
	s_cselect_b32 s18, s62, s18
	s_cselect_b32 s17, s63, s17
	s_mul_i32 s63, s56, 13
	s_lshr_b32 s63, s63, 6
	s_mul_i32 s62, s63, 5
	s_sub_i32 s62, s56, s62
	s_add_i32 s62, s62, 27
	s_cmpk_lt_u32 s56, 20
	s_cselect_b32 s18, s62, s18
	s_cselect_b32 s17, s63, s17
	s_sub_i32 s7, 64, s9
	s_cmp_gt_u32 s7, s19
	s_cselect_b32 s16, 2, 1
	s_cmp_gt_u32 s7, s20
	v_writelane_b32 v244, s9, 40
	s_cselect_b64 s[8:9], -1, 0
	s_cmp_lg_u64 s[8:9], 0
	s_addc_u32 s8, s16, 0
	s_bfe_i64 s[6:7], s[6:7], 0x100000
	s_lshl_b64 s[6:7], s[6:7], 19
	v_writelane_b32 v244, s6, 41
	s_ashr_i32 s19, s18, 31
	s_ashr_i32 s31, s30, 31
	v_writelane_b32 v244, s7, 42
	s_lshl_b32 s6, s15, 7
	v_writelane_b32 v244, s6, 43
	v_writelane_b32 v244, s17, 44
	s_lshl_b32 s6, s17, 21
	v_writelane_b32 v244, s6, 45
	s_mov_b32 s6, s18
	v_writelane_b32 v244, s6, 46
	v_cvt_f32_ubyte0_e32 v1, s12
	v_rcp_iflag_f32_e32 v2, v1
	v_writelane_b32 v244, s7, 47
	s_lshl_b64 s[6:7], s[18:19], 21
	v_writelane_b32 v244, s6, 48
	s_nop 1
	v_writelane_b32 v244, s7, 49
	s_mov_b32 s6, s30
	v_writelane_b32 v244, s6, 50
	s_nop 1
	v_writelane_b32 v244, s7, 51
	s_lshl_b64 s[6:7], s[30:31], 19
	v_writelane_b32 v244, s6, 52
	s_cmp_eq_u32 s15, 0
	s_nop 0
	v_writelane_b32 v244, s7, 53
	s_cselect_b32 s6, s8, 0
	v_writelane_b32 v244, s6, 54
	s_sext_i32_i16 s6, s10
	v_cvt_f32_i32_e32 v0, s6
	s_cselect_b32 s7, 2, 1
	s_ashr_i32 s6, s6, 30
	v_writelane_b32 v244, s7, 55
	v_mul_f32_e32 v2, v0, v2
	v_trunc_f32_e32 v2, v2
	v_fma_f32 v0, -v2, v1, v0
	s_or_b32 s8, s6, 1
	v_cmp_ge_f32_e64 s[6:7], |v0|, v1
	v_cvt_i32_f32_e32 v0, v2
	s_and_b64 s[6:7], s[6:7], exec
	s_cselect_b32 s6, s8, 0
	v_cvt_f32_ubyte0_e32 v1, s22
	v_readfirstlane_b32 s7, v0
	s_add_i32 s15, s7, s6
	s_mul_i32 s6, s15, s12
	s_sub_i32 s6, s10, s6
	s_sext_i32_i16 s6, s6
	s_add_i32 s6, s11, s6
	v_writelane_b32 v244, s6, 56
	s_sext_i32_i16 s6, s13
	v_cvt_f32_i32_e32 v0, s6
	v_rcp_iflag_f32_e32 v2, v1
	s_ashr_i32 s6, s6, 30
	s_or_b32 s8, s6, 1
	v_mul_f32_e32 v2, v0, v2
	v_trunc_f32_e32 v2, v2
	v_fma_f32 v0, -v2, v1, v0
	v_cmp_ge_f32_e64 s[6:7], |v0|, v1
	v_cvt_i32_f32_e32 v0, v2
	s_and_b64 s[6:7], s[6:7], exec
	s_cselect_b32 s6, s8, 0
	v_cvt_f32_ubyte0_e32 v1, s24
	v_readfirstlane_b32 s7, v0
	s_add_i32 s6, s7, s6
	s_mul_i32 s7, s6, s22
	s_sub_i32 s7, s13, s7
	s_sext_i32_i8 s7, s7
	s_add_i32 s10, s5, s7
	s_sext_i32_i16 s5, s14
	v_cvt_f32_i32_e32 v0, s5
	v_rcp_iflag_f32_e32 v2, v1
	s_bfe_i64 s[8:9], s[6:7], 0x80000
	s_lshl_b64 s[8:9], s[8:9], 18
	v_writelane_b32 v244, s8, 57
	s_ashr_i32 s11, s10, 31
	v_mul_f32_e32 v2, v0, v2
	v_writelane_b32 v244, s9, 58
	s_mov_b32 s8, s10
	v_writelane_b32 v244, s8, 59
	v_trunc_f32_e32 v2, v2
	v_fma_f32 v0, -v2, v1, v0
	v_writelane_b32 v244, s9, 60
	s_lshl_b64 s[8:9], s[10:11], 18
	v_writelane_b32 v244, s8, 61
	s_ashr_i32 s5, s5, 30
	s_or_b32 s5, s5, 1
	v_writelane_b32 v244, s9, 62
	v_cmp_ge_f32_e64 s[8:9], |v0|, v1
	v_cvt_i32_f32_e32 v0, v2
	s_and_b64 s[8:9], s[8:9], exec
	v_writelane_b32 v244, s26, 63
	s_sext_i32_i8 s6, s6
	s_cselect_b32 s5, s5, 0
	v_writelane_b32 v243, s27, 0
	v_writelane_b32 v243, s6, 1
	v_readfirstlane_b32 s6, v0
	s_add_i32 s6, s6, s5
	s_mul_i32 s5, s6, s24
	s_sub_i32 s5, s14, s5
	s_sext_i32_i8 s5, s5
	s_add_i32 s5, s23, s5
	s_mul_i32 s7, s95, s94
	v_writelane_b32 v243, s5, 2
	s_sext_i32_i16 s5, s15
	s_mul_i32 s95, s7, s33
	v_writelane_b32 v243, s5, 3
	s_sext_i32_i8 s5, s6
	s_bfe_i64 s[6:7], s[6:7], 0x80000
	v_writelane_b32 v243, s5, 4
	s_lshl_b64 s[6:7], s[6:7], 19
	v_writelane_b32 v243, s6, 5
	s_ashr_i32 s5, s4, 31
	s_lshl_b64 s[4:5], s[4:5], 19
	v_writelane_b32 v243, s7, 6
	v_writelane_b32 v243, s4, 7
	s_lshl_b64 s[0:1], s[0:1], 2
	s_ashr_i32 s85, s84, 31
	v_writelane_b32 v243, s5, 8
	v_writelane_b32 v243, s0, 9
	s_lshl_b32 s4, s94, 5
	v_mbcnt_lo_u32_b32 v0, -1, 0
	v_writelane_b32 v243, s1, 10
	v_writelane_b32 v243, s84, 11
	s_add_i32 s1, s84, 0xfffff800
	s_movk_i32 s0, 0x110
	v_writelane_b32 v243, s85, 12
	v_writelane_b32 v243, s1, 13
	s_lshl_b32 s1, s2, 5
	v_writelane_b32 v243, s1, 14
	s_addk_i32 s1, 0xdc00
	v_writelane_b32 v243, s1, 15
	v_writelane_b32 v243, s4, 16
	s_add_i32 s1, s4, 0xfffffc00
	v_writelane_b32 v243, s1, 17
	s_lshl_b32 s1, s94, 10
	v_writelane_b32 v243, s1, 18
	s_lshl_b32 s1, s2, 12
	v_writelane_b32 v243, s1, 19
	s_lshl_b32 s1, s94, 14
	v_writelane_b32 v243, s1, 20
	s_add_i32 s1, 0, 0x20000
	v_writelane_b32 v243, s1, 21
	s_add_i32 s1, 0, 0x20004
	v_writelane_b32 v243, s1, 22
	v_cmp_gt_i32_e64 s[0:1], s0, v214
	v_cndmask_b32_e64 v215, 0, 1, s[26:27]
	v_mbcnt_hi_u32_b32 v221, -1, v0
	v_writelane_b32 v243, s0, 23
	s_movk_i32 s33, 0x2000
	s_mov_b32 s84, s28
	v_writelane_b32 v243, s1, 24
	v_cmp_gt_u32_e64 s[0:1], 64, v195
	s_mov_b64 s[4:5], 0x80
	s_nop 0
	v_writelane_b32 v243, s0, 25
	s_nop 1
	v_writelane_b32 v243, s1, 26
	s_lshl_b64 s[0:1], s[54:55], 2
	v_writelane_b32 v243, s0, 27
	s_nop 1
	v_writelane_b32 v243, s1, 28
	v_writelane_b32 v243, s36, 29
	s_nop 1
	v_writelane_b32 v243, s37, 30
	v_writelane_b32 v243, s38, 31
	s_nop 1
	v_writelane_b32 v243, s39, 32
	v_writelane_b32 v243, s40, 33
	s_nop 1
	v_writelane_b32 v243, s41, 34
	v_writelane_b32 v243, s42, 35
	s_nop 1
	v_writelane_b32 v243, s43, 36
	v_writelane_b32 v243, s44, 37
	s_nop 1
	v_writelane_b32 v243, s45, 38
	v_writelane_b32 v243, s46, 39
	s_nop 1
	v_writelane_b32 v243, s47, 40
	v_writelane_b32 v243, s48, 41
	s_nop 1
	v_writelane_b32 v243, s49, 42
	v_writelane_b32 v243, s94, 43
	s_nop 1
	v_writelane_b32 v243, s95, 44
	v_writelane_b32 v243, s82, 45
	s_nop 1
	v_writelane_b32 v243, s83, 46
	v_writelane_b32 v243, s86, 47
	v_writelane_b32 v243, s80, 48
	v_writelane_b32 v243, s81, 49
	v_writelane_b32 v243, s87, 50
	v_writelane_b32 v243, s89, 51
	v_writelane_b32 v243, s95, 52
	s_branch .LBB0_414
